# init phase: H rows written through (sc1) like the LayerNorm's
# speedup vs baseline: 1.0029x; 1.0017x over previous
.Linit_nocopy:
	global_load_dwordx4 v[12:15], v[14:15], off
	s_nop 0
	global_load_dwordx4 v[16:19], v[16:17], off
	s_waitcnt vmcnt(1)
	v_pk_add_f32 v[14:15], v[14:15], 1.0 op_sel_hi:[1,0]
	v_pk_add_f32 v[12:13], v[12:13], 1.0 op_sel_hi:[1,0]
	s_waitcnt vmcnt(0)
	v_pk_fma_f32 v[10:11], v[10:11], v[14:15], v[18:19]
	v_pk_fma_f32 v[8:9], v[8:9], v[12:13], v[16:17]
	s_nop 0
	v_cvt_pk_bf16_f32 v8, v8, v9
	v_cvt_pk_bf16_f32 v9, v10, v11
	global_store_dwordx2 v[4:5], v[8:9], off sc1
	v_lshl_add_u64 v[4:5], v[4:5], 0, s[20:21]
	s_andn2_b64 exec, exec, s[40:41]
	s_cbranch_execnz .LBB0_40
